# attention softmax-then-MFMA role: QK MFMAs (with bookkeeping) issued before the PV MFMAs
# speedup vs baseline: 1.0068x; 1.0034x over previous
; #define MFMA16(a, b, c) __builtin_amdgcn_mfma_f32_16x16x32_f16((a), (b), (c), 0, 0, 0)
; #define LAS __attribute__((address_space(3)))
; template <bool SEL, bool GEN>
; DI void attn_step(const KF& kv, const int kb, const int t, const int lane, const bool selbit,
;                   const LAS float* tabh, const half8 (&q)[2][2], f32x4 (&O)[2][4], const float (&nR)[2], float (&l)[2]) {
;   const int fq = lane >> 4;
;   f32x4 s[2][2];
; #pragma unroll
;   for (int hp = 0; hp < 2; ++hp) {
;     float nm = nR[hp];
;     if (SEL) nm = selbit ? nm : MASKV;
;     const f32x4 c0 = {nm, nm, nm, nm};
; #pragma unroll
;     for (int kt = 0; kt < 2; ++kt) {
;       s[hp][kt] = MFMA16(kv.k[kt][0], q[hp][0], c0);
;       s[hp][kt] = MFMA16(kv.k[kt][1], q[hp][1], s[hp][kt]);
;     }
;   }
;   if (GEN) {
;     const int d0 = t - kb - fq * 4;
; #pragma unroll
;     for (int kt = 0; kt < 2; ++kt)
; #pragma unroll
;       for (int j = 0; j < 4; ++j) {
;         const int dist = d0 - (kt * 16 + j);
;         const bool bad = SEL ? (dist < 0) : ((unsigned)dist >= 512u);
;         const int ix = bad ? 130 : (dist > 128 ? 128 : dist);
; #pragma unroll
;         for (int hp = 0; hp < 2; ++hp) s[hp][kt][j] += tabh[hp * 132 + ix];
;       }
;   }
;   half8 pf[2];
; #pragma unroll
;   for (int hp = 0; hp < 2; ++hp) {
;     f32x4 p0, p1;
; #pragma unroll
;     for (int j = 0; j < 4; ++j) { p0[j] = __builtin_amdgcn_exp2f(s[hp][0][j]); p1[j] = __builtin_amdgcn_exp2f(s[hp][1][j]); }
;     l[hp] += ((p0[0] + p0[1]) + (p0[2] + p0[3])) + ((p1[0] + p1[1]) + (p1[2] + p1[3]));
;     pf[hp] = pack8(p0, p1);
;   }
; #pragma unroll
;   for (int dt = 0; dt < 4; ++dt)
; #pragma unroll
;     for (int hp = 0; hp < 2; ++hp) O[hp][dt] = MFMA16(kv.v[dt], pf[hp], O[hp][dt]);
.Lat_noga_xa:
	v_exp_f32_e32 v198, v100
	v_exp_f32_e32 v199, v101
	v_exp_f32_e32 v200, v102
	v_exp_f32_e32 v201, v103
	v_exp_f32_e32 v202, v104
	v_exp_f32_e32 v203, v105
	v_exp_f32_e32 v204, v106
	v_exp_f32_e32 v205, v107
	v_exp_f32_e32 v206, v108
	v_exp_f32_e32 v207, v109
	v_exp_f32_e32 v208, v110
	v_exp_f32_e32 v209, v111
	v_exp_f32_e32 v210, v112
	v_exp_f32_e32 v211, v113
	v_exp_f32_e32 v212, v114
	v_exp_f32_e32 v213, v115
	v_cvt_pkrtz_f16_f32 v120, v198, v199
	v_cvt_pkrtz_f16_f32 v121, v200, v201
	v_cvt_pkrtz_f16_f32 v122, v202, v203
	v_cvt_pkrtz_f16_f32 v123, v204, v205
	v_cvt_pkrtz_f16_f32 v124, v206, v207
	v_cvt_pkrtz_f16_f32 v125, v208, v209
	v_cvt_pkrtz_f16_f32 v126, v210, v211
	v_cvt_pkrtz_f16_f32 v127, v212, v213
	s_waitcnt lgkmcnt(0)
	s_and_b32 s44, s12, 2
	s_or_b32 s44, s44, 1
	v_mfma_f32_16x16x32_f16 v[100:103], v[96:99], v[8:11], v[128:131]
	s_add_i32 s8, s45, 64
	s_min_i32 s8, s8, s14
	s_mul_i32 s8, s8, s42
	s_mov_b32 s9, 0
	v_lshl_add_u64 v[238:239], v[240:241], 0, s[8:9]
	v_mfma_f32_16x16x32_f16 v[104:107], v[88:91], v[8:11], v[128:131]
	s_add_i32 m0, s43, s22
	s_nop 0
	global_load_lds_dwordx4 v[238:239], off
	s_add_i32 s43, s43, 0x2000
	s_cmp_eq_u32 s43, 0x1f880
	v_mfma_f32_16x16x32_f16 v[108:111], v[96:99], v[16:19], v[132:135]
	s_cselect_b32 s43, 0x20080, s43
	s_cmp_eq_u32 s43, 0x22080
	s_cselect_b32 s43, 0x19880, s43
	s_add_i32 s39, s39, 0x2000
	s_cmp_eq_u32 s39, 0x1f880
	v_mfma_f32_16x16x32_f16 v[112:115], v[88:91], v[16:19], v[132:135]
	s_cselect_b32 s39, 0x20080, s39
	s_cmp_eq_u32 s39, 0x22080
	s_cselect_b32 s39, 0x19880, s39
	s_add_i32 s45, s45, 32
	s_add_i32 s41, s41, -1
	v_mfma_f32_16x16x32_f16 v[100:103], v[92:95], v[12:15], v[100:103]
	s_add_i32 s10, s45, 0x9f
	s_cmp_gt_i32 s10, s51
	s_cselect_b32 s11, 2, 0
	s_add_i32 s10, s45, 0x1f1
	s_cmp_le_i32 s10, s51
	v_mfma_f32_16x16x32_f16 v[104:107], v[84:87], v[12:15], v[104:107]
	s_cselect_b32 s10, 2, 0
	s_and_b32 s10, s10, s4
	s_or_b32 s11, s11, s10
	s_lshr_b32 s10, s45, 6
	v_bfe_u32 v0, v244, s10, 1
	v_mfma_f32_16x16x32_f16 v[108:111], v[92:95], v[20:23], v[108:111]
	v_cmp_ne_u32_e32 vcc, 0, v0
	s_cmp_lg_u64 vcc, 0
	s_cselect_b32 s10, 1, 0
	s_lshr_b32 s9, s11, 1
	s_or_b32 s10, s10, s9
	v_mfma_f32_16x16x32_f16 v[112:115], v[84:87], v[20:23], v[112:115]
	s_cmp_le_i32 s45, s15
	s_cselect_b32 s10, s10, 0
	s_cmp_ge_i32 s45, s40
	s_cselect_b32 s10, s10, 0
	s_or_b32 s12, s11, s10
	v_mfma_f32_16x16x32_f16 v[60:63], v[80:83], v[120:123], v[60:63]
	v_add_f32_e32 v214, v214, v198
	v_add_f32_e32 v215, v215, v199
	v_mfma_f32_16x16x32_f16 v[56:59], v[76:79], v[120:123], v[56:59]
	v_add_f32_e32 v216, v216, v200
	v_add_f32_e32 v217, v217, v201
	v_mfma_f32_16x16x32_f16 v[52:55], v[72:75], v[120:123], v[52:55]
	v_add_f32_e32 v214, v214, v202
	v_add_f32_e32 v215, v215, v203
	v_mfma_f32_16x16x32_f16 v[48:51], v[68:71], v[120:123], v[48:51]
	v_add_f32_e32 v216, v216, v204
	v_add_f32_e32 v217, v217, v205
	v_mfma_f32_16x16x32_f16 v[44:47], v[80:83], v[124:127], v[44:47]
	v_add_f32_e32 v218, v218, v206
	v_add_f32_e32 v219, v219, v207
	v_mfma_f32_16x16x32_f16 v[40:43], v[76:79], v[124:127], v[40:43]
	v_add_f32_e32 v220, v220, v208
	v_add_f32_e32 v221, v221, v209
	v_mfma_f32_16x16x32_f16 v[36:39], v[72:75], v[124:127], v[36:39]
	v_add_f32_e32 v218, v218, v210
	v_add_f32_e32 v219, v219, v211
	v_mfma_f32_16x16x32_f16 v[32:35], v[68:71], v[124:127], v[32:35]
	v_add_f32_e32 v220, v220, v212
	v_add_f32_e32 v221, v221, v213
	ds_read_b128 v[80:83], v65 offset:4096
	ds_read_b128 v[76:79], v65 offset:5120
	ds_read_b128 v[72:75], v65 offset:6144
	ds_read_b128 v[68:71], v65 offset:7168
	s_cmp_lg_u32 s41, 0
	s_cbranch_scc1 .Lat_xtop
	s_branch .Lat_xexit
